# grid-barrier closing s_barrier moved below next GEMM phase's weight-tile LDS-DMA (G3,G4,G5): weights stream in during the barrier
# speedup vs baseline: 1.0041x; 1.0004x over previous
.LBB0_662:
	s_or_b64 exec, exec, s[10:11]
	s_mov_b64 s[10:11], s[0:1]
	v_mov_b32_e32 v0, v232
	v_mov_b32_e32 v15, v232
	s_waitcnt lgkmcnt(0)
	s_and_b64 vcc, exec, s[6:7]
	v_readfirstlane_b32 s20, v15
	s_cbranch_vccnz .Lg3_skipbar
	v_lshlrev_b32_e32 v2, 4, v15
	v_add_u32_e32 v3, 0x2000, v2
	v_ashrrev_i32_e32 v0, 31, v3
	v_lshrrev_b32_e32 v0, 22, v0
	v_add_u32_e32 v0, v3, v0
	v_ashrrev_i32_e32 v0, 10, v0
	s_load_dwordx2 s[10:11], s[10:11], 0x90
	v_mul_i32_i24_e32 v4, 0x400, v0
	v_sub_u32_e32 v3, v3, v4
	v_lshrrev_b32_e32 v4, 4, v3
	v_bitop3_b32 v3, v4, v3, 32 bitop3:0x6c
	v_ashrrev_i32_e32 v4, 31, v3
	s_waitcnt lgkmcnt(0)
	s_add_u32 s42, s10, 0x4200000
	v_lshrrev_b32_e32 v4, 26, v4
	s_addc_u32 s43, s11, 0
	v_add_u32_e32 v4, v3, v4
	v_lshlrev_b32_e32 v5, 3, v0
	s_add_u32 s4, s10, s84
	v_readlane_b32 s5, v255, 51
	v_ashrrev_i32_e32 v10, 6, v4
	v_and_b32_e32 v5, -16, v5
	s_addc_u32 s5, s11, s5
	v_add_u32_e32 v5, v10, v5
	s_add_u32 s44, s4, 0x900000
	v_and_b32_e32 v6, 3, v10
	s_mov_b32 s4, 0x1fffe0
	v_lshrrev_b32_e32 v7, 2, v5
	v_lshlrev_b32_e32 v8, 1, v5
	v_and_b32_e32 v4, 0xc0, v4
	v_and_or_b32 v6, v5, s4, v6
	v_and_b32_e32 v7, 4, v7
	v_and_b32_e32 v8, 24, v8
	v_sub_u32_e32 v3, v3, v4
	v_or3_b32 v6, v6, v7, v8
	v_lshlrev_b32_e32 v7, 5, v0
	v_ashrrev_i16_sdwa v3, v247, sext(v3) dst_sel:DWORD dst_unused:UNUSED_PAD src0_sel:DWORD src1_sel:BYTE_0
	v_and_b32_e32 v7, 32, v7
	v_bfe_i32 v11, v3, 0, 16
	v_add_lshl_u32 v3, v7, v11, 1
	v_lshl_add_u32 v130, v6, 11, v3
	v_lshl_add_u32 v132, v5, 11, v3
	v_bfe_i32 v3, v15, 27, 1
	v_lshrrev_b32_e32 v3, 22, v3
	v_add_u32_e32 v3, v2, v3
	v_and_b32_e32 v3, 0xfffffc00, v3
	v_sub_u32_e32 v2, v2, v3
	v_lshrrev_b32_e32 v3, 4, v2
	v_bitop3_b32 v3, v3, v2, 32 bitop3:0x6c
	v_ashrrev_i32_e32 v2, 31, v2
	v_lshrrev_b32_e32 v2, 26, v2
	v_add_u32_e32 v2, v3, v2
	v_ashrrev_i32_e32 v12, 6, v2
	v_ashrrev_i32_e32 v2, 31, v15
	v_lshrrev_b32_e32 v2, 26, v2
	v_add_u32_e32 v2, v15, v2
	v_ashrrev_i32_e32 v13, 6, v2
	v_lshlrev_b32_e32 v2, 3, v13
	v_and_b32_e32 v2, -16, v2
	v_add_u32_e32 v2, v12, v2
	v_and_b32_e32 v4, 3, v12
	v_lshrrev_b32_e32 v5, 2, v2
	v_lshlrev_b32_e32 v6, 1, v2
	v_and_or_b32 v4, v2, s4, v4
	v_and_b32_e32 v5, 4, v5
	v_and_b32_e32 v6, 24, v6
	v_or3_b32 v4, v4, v5, v6
	v_mul_i32_i24_e32 v6, 64, v12
	s_addc_u32 s45, s5, 0
	s_ashr_i32 s22, s20, 6
	v_sub_u32_e32 v3, v3, v6
	s_ashr_i32 s21, s20, 8
	s_lshl_b32 s51, s22, 10
	v_lshlrev_b32_e32 v5, 5, v13
	v_ashrrev_i16_sdwa v3, v247, sext(v3) dst_sel:DWORD dst_unused:UNUSED_PAD src0_sel:DWORD src1_sel:BYTE_0
	v_readlane_b32 s4, v255, 41
	v_and_b32_e32 v5, 32, v5
	v_bfe_i32 v14, v3, 0, 16
	v_readlane_b32 s5, v255, 42
	s_add_u32 s34, s44, s4
	v_add_lshl_u32 v3, v5, v14, 1
	s_addc_u32 s35, s45, s5
	s_add_i32 s55, s51, 0
	v_lshl_add_u32 v134, v4, 11, v3
	s_add_i32 m0, s55, 0x10000
	v_readlane_b32 s4, v255, 45
	global_load_lds_dwordx4 v134, s[34:35]
	s_add_i32 m0, s55, 0x12000
	s_add_u32 s12, s34, 0x40000
	global_load_lds_dwordx4 v130, s[34:35]
	s_addc_u32 s13, s35, 0
	s_add_i32 m0, s55, 0x14000
	v_readlane_b32 s5, v255, 46
	global_load_lds_dwordx4 v134, s[12:13]
	s_add_i32 m0, s55, 0x16000
	s_add_u32 s30, s42, s4
	s_addc_u32 s31, s43, s5
	s_add_i32 s56, s55, 0x2000
	v_lshl_add_u32 v136, v2, 11, v3
	global_load_lds_dwordx4 v130, s[12:13]
	s_barrier
	s_mov_b32 m0, s55
	s_add_u32 s12, s30, 0x40000
	global_load_lds_dwordx4 v136, s[30:31]
	s_mov_b32 m0, s56
	s_addc_u32 s13, s31, 0
	s_add_i32 s57, s55, 0x4000
	global_load_lds_dwordx4 v132, s[30:31]
	s_mov_b32 m0, s57
	s_add_i32 s58, s55, 0x6000
	global_load_lds_dwordx4 v136, s[12:13]
	s_mov_b32 m0, s58
	v_mov_b32_e32 v135, v1
	global_load_lds_dwordx4 v132, s[12:13]
	v_mov_b32_e32 v131, v1
	v_mov_b32_e32 v137, v1
	v_mov_b32_e32 v133, v1
	s_cmp_eq_u32 s21, 1
	v_lshl_add_u64 v[8:9], s[34:35], 0, v[134:135]
	v_lshl_add_u64 v[6:7], s[34:35], 0, v[130:131]
	v_lshl_add_u64 v[2:3], s[30:31], 0, v[136:137]
	s_cselect_b64 s[12:13], -1, 0
	s_cmp_lg_u32 s21, 1
	v_lshl_add_u64 v[4:5], s[30:31], 0, v[132:133]
	s_cbranch_scc1 .LBB0_665
	s_barrier

.Lg3_skipbar:
	s_barrier
	s_branch .LBB0_698

.LBB0_760:
	s_or_b64 exec, exec, s[8:9]
	s_ashr_i32 s55, s54, 31
	s_lshl_b64 s[10:11], s[54:55], 14
	s_mov_b64 s[8:9], s[0:1]
	v_mov_b32_e32 v0, v232
	s_add_u32 s10, s10, 0x8000
	v_mov_b32_e32 v16, v232
	s_waitcnt lgkmcnt(0)
	s_addc_u32 s11, s11, 0
	s_and_b64 vcc, exec, s[6:7]
	v_readfirstlane_b32 s18, v16
	s_cbranch_vccnz .Lg4_skipbar
	v_lshlrev_b32_e32 v0, 4, v16
	v_add_u32_e32 v2, 0x2000, v0
	v_ashrrev_i32_e32 v3, 31, v2
	v_lshrrev_b32_e32 v3, 22, v3
	v_add_u32_e32 v3, v2, v3
	v_ashrrev_i32_e32 v10, 10, v3
	s_load_dwordx2 s[8:9], s[8:9], 0x90
	v_mul_i32_i24_e32 v3, 0x400, v10
	v_sub_u32_e32 v2, v2, v3
	v_lshrrev_b32_e32 v3, 4, v2
	v_bitop3_b32 v2, v3, v2, 32 bitop3:0x6c
	v_ashrrev_i32_e32 v3, 31, v2
	s_waitcnt lgkmcnt(0)
	s_add_u32 s42, s8, 0x8200000
	v_lshrrev_b32_e32 v3, 26, v3
	s_addc_u32 s43, s9, 0
	v_add_u32_e32 v3, v2, v3
	v_lshlrev_b32_e32 v4, 3, v10
	s_add_u32 s4, s8, s84
	v_readlane_b32 s5, v255, 51
	v_ashrrev_i32_e32 v11, 6, v3
	v_and_b32_e32 v4, -16, v4
	s_addc_u32 s5, s9, s5
	v_add_u32_e32 v4, v11, v4
	s_add_u32 s44, s4, 0xf00000
	v_and_b32_e32 v5, 3, v11
	s_mov_b32 s4, 0x1fffe0
	v_lshrrev_b32_e32 v6, 2, v4
	v_lshlrev_b32_e32 v7, 1, v4
	v_and_b32_e32 v3, 0xc0, v3
	v_and_or_b32 v5, v4, s4, v5
	v_and_b32_e32 v6, 4, v6
	v_and_b32_e32 v7, 24, v7
	v_sub_u32_e32 v2, v2, v3
	v_or3_b32 v5, v5, v6, v7
	v_lshlrev_b32_e32 v6, 5, v10
	v_ashrrev_i16_sdwa v2, v247, sext(v2) dst_sel:DWORD dst_unused:UNUSED_PAD src0_sel:DWORD src1_sel:BYTE_0
	v_and_b32_e32 v6, 32, v6
	v_bfe_i32 v12, v2, 0, 16
	v_add_lshl_u32 v2, v6, v12, 1
	v_lshl_add_u32 v190, v5, 11, v2
	v_lshl_add_u32 v192, v4, 11, v2
	v_bfe_i32 v2, v16, 27, 1
	v_lshrrev_b32_e32 v2, 22, v2
	v_add_u32_e32 v2, v0, v2
	v_and_b32_e32 v2, 0xfffffc00, v2
	v_sub_u32_e32 v0, v0, v2
	v_lshrrev_b32_e32 v2, 4, v0
	v_bitop3_b32 v2, v2, v0, 32 bitop3:0x6c
	v_ashrrev_i32_e32 v0, 31, v0
	v_lshrrev_b32_e32 v0, 26, v0
	v_add_u32_e32 v0, v2, v0
	v_ashrrev_i32_e32 v13, 6, v0
	v_ashrrev_i32_e32 v0, 31, v16
	v_lshrrev_b32_e32 v0, 26, v0
	v_add_u32_e32 v0, v16, v0
	v_ashrrev_i32_e32 v14, 6, v0
	v_lshlrev_b32_e32 v0, 3, v14
	v_and_b32_e32 v0, -16, v0
	v_add_u32_e32 v3, v13, v0
	v_and_b32_e32 v0, 3, v13
	v_lshrrev_b32_e32 v4, 2, v3
	v_lshlrev_b32_e32 v5, 1, v3
	v_and_or_b32 v0, v3, s4, v0
	v_and_b32_e32 v4, 4, v4
	v_and_b32_e32 v5, 24, v5
	v_or3_b32 v0, v0, v4, v5
	v_mul_i32_i24_e32 v5, 64, v13
	s_addc_u32 s45, s5, 0
	s_ashr_i32 s19, s18, 6
	v_sub_u32_e32 v2, v2, v5
	s_ashr_i32 s20, s18, 8
	s_lshl_b32 s51, s19, 10
	v_lshlrev_b32_e32 v4, 5, v14
	v_ashrrev_i16_sdwa v2, v247, sext(v2) dst_sel:DWORD dst_unused:UNUSED_PAD src0_sel:DWORD src1_sel:BYTE_0
	v_readlane_b32 s4, v255, 41
	v_and_b32_e32 v4, 32, v4
	v_bfe_i32 v15, v2, 0, 16
	v_readlane_b32 s5, v255, 42
	s_add_u32 s34, s44, s4
	v_add_lshl_u32 v2, v4, v15, 1
	s_addc_u32 s35, s45, s5
	s_add_i32 s56, s51, 0
	v_lshl_add_u32 v0, v0, 11, v2
	s_add_i32 m0, s56, 0x10000
	v_readlane_b32 s4, v255, 45
	global_load_lds_dwordx4 v0, s[34:35]
	s_add_i32 m0, s56, 0x12000
	s_add_u32 s12, s34, 0x40000
	global_load_lds_dwordx4 v190, s[34:35]
	s_addc_u32 s13, s35, 0
	s_add_i32 m0, s56, 0x14000
	v_readlane_b32 s5, v255, 46
	global_load_lds_dwordx4 v0, s[12:13]
	s_add_i32 m0, s56, 0x16000
	s_add_u32 s30, s42, s4
	s_addc_u32 s31, s43, s5
	s_add_i32 s57, s56, 0x2000
	v_lshl_add_u32 v202, v3, 11, v2
	global_load_lds_dwordx4 v190, s[12:13]
	s_barrier
	s_mov_b32 m0, s56
	s_add_u32 s12, s30, 0x40000
	global_load_lds_dwordx4 v202, s[30:31]
	s_mov_b32 m0, s57
	s_addc_u32 s13, s31, 0
	s_add_i32 s58, s56, 0x4000
	global_load_lds_dwordx4 v192, s[30:31]
	s_mov_b32 m0, s58
	s_add_i32 s59, s56, 0x6000
	global_load_lds_dwordx4 v202, s[12:13]
	s_mov_b32 m0, s59
	v_mov_b32_e32 v191, v1
	global_load_lds_dwordx4 v192, s[12:13]
	v_mov_b32_e32 v203, v1
	v_mov_b32_e32 v193, v1
	s_cmp_eq_u32 s20, 1
	v_lshl_add_u64 v[8:9], s[34:35], 0, v[0:1]
	v_lshl_add_u64 v[6:7], s[34:35], 0, v[190:191]
	v_lshl_add_u64 v[2:3], s[30:31], 0, v[202:203]
	s_cselect_b64 s[12:13], -1, 0
	s_cmp_lg_u32 s20, 1
	v_lshl_add_u64 v[4:5], s[30:31], 0, v[192:193]
	s_cbranch_scc1 .LBB0_763
	s_barrier

.LBB0_848:
	s_or_b64 exec, exec, s[8:9]
	v_readlane_b32 s4, v255, 11
	s_mov_b64 s[8:9], s[0:1]
	v_mov_b32_e32 v0, v232
	s_lshl_b32 s14, s50, 12
	v_mov_b32_e32 v150, v232
	v_readlane_b32 s5, v255, 12
	s_waitcnt lgkmcnt(0)
	s_ashr_i32 s15, s14, 31
	s_andn2_b64 vcc, exec, s[4:5]
	v_readfirstlane_b32 s20, v150
	s_cbranch_vccnz .Lg5_skipbar
	v_lshlrev_b32_e32 v2, 4, v150
	v_add_u32_e32 v3, 0x2000, v2
	v_ashrrev_i32_e32 v0, 31, v3
	v_lshrrev_b32_e32 v0, 22, v0
	v_add_u32_e32 v0, v3, v0
	v_ashrrev_i32_e32 v0, 10, v0
	s_load_dwordx2 s[12:13], s[8:9], 0x90
	v_mul_i32_i24_e32 v4, 0x400, v0
	v_sub_u32_e32 v3, v3, v4
	v_lshrrev_b32_e32 v4, 4, v3
	v_bitop3_b32 v3, v4, v3, 32 bitop3:0x6c
	v_ashrrev_i32_e32 v4, 31, v3
	s_waitcnt lgkmcnt(0)
	s_add_u32 s42, s12, 0x4200000
	v_lshrrev_b32_e32 v4, 26, v4
	s_addc_u32 s43, s13, 0
	v_add_u32_e32 v4, v3, v4
	v_lshlrev_b32_e32 v5, 3, v0
	s_add_u32 s4, s12, s84
	v_readlane_b32 s5, v255, 51
	v_ashrrev_i32_e32 v10, 6, v4
	v_and_b32_e32 v5, -16, v5
	s_addc_u32 s5, s13, s5
	v_add_u32_e32 v5, v10, v5
	s_add_u32 s44, s4, 0x1100000
	v_and_b32_e32 v6, 3, v10
	s_mov_b32 s4, 0x1fffe0
	v_lshrrev_b32_e32 v7, 2, v5
	v_lshlrev_b32_e32 v8, 1, v5
	v_and_b32_e32 v4, 0xc0, v4
	v_and_or_b32 v6, v5, s4, v6
	v_and_b32_e32 v7, 4, v7
	v_and_b32_e32 v8, 24, v8
	v_sub_u32_e32 v3, v3, v4
	v_or3_b32 v6, v6, v7, v8
	v_lshlrev_b32_e32 v7, 5, v0
	v_ashrrev_i16_sdwa v3, v247, sext(v3) dst_sel:DWORD dst_unused:UNUSED_PAD src0_sel:DWORD src1_sel:BYTE_0
	v_and_b32_e32 v7, 32, v7
	v_bfe_i32 v11, v3, 0, 16
	v_add_lshl_u32 v3, v7, v11, 1
	v_lshl_add_u32 v130, v6, 11, v3
	v_lshl_add_u32 v132, v5, 11, v3
	v_bfe_i32 v3, v150, 27, 1
	v_lshrrev_b32_e32 v3, 22, v3
	v_add_u32_e32 v3, v2, v3
	v_and_b32_e32 v3, 0xfffffc00, v3
	v_sub_u32_e32 v2, v2, v3
	v_lshrrev_b32_e32 v3, 4, v2
	v_bitop3_b32 v3, v3, v2, 32 bitop3:0x6c
	v_ashrrev_i32_e32 v2, 31, v2
	v_lshrrev_b32_e32 v2, 26, v2
	v_add_u32_e32 v2, v3, v2
	v_ashrrev_i32_e32 v12, 6, v2
	v_ashrrev_i32_e32 v2, 31, v150
	v_lshrrev_b32_e32 v2, 26, v2
	v_add_u32_e32 v2, v150, v2
	v_ashrrev_i32_e32 v13, 6, v2
	v_lshlrev_b32_e32 v2, 3, v13
	v_and_b32_e32 v2, -16, v2
	v_add_u32_e32 v2, v12, v2
	v_and_b32_e32 v4, 3, v12
	v_lshrrev_b32_e32 v5, 2, v2
	v_lshlrev_b32_e32 v6, 1, v2
	v_and_or_b32 v4, v2, s4, v4
	v_and_b32_e32 v5, 4, v5
	v_and_b32_e32 v6, 24, v6
	v_or3_b32 v4, v4, v5, v6
	v_mul_i32_i24_e32 v6, 64, v12
	s_addc_u32 s45, s5, 0
	s_ashr_i32 s8, s20, 6
	v_sub_u32_e32 v3, v3, v6
	s_ashr_i32 s9, s20, 8
	s_lshl_b32 s51, s8, 10
	v_lshlrev_b32_e32 v5, 5, v13
	v_ashrrev_i16_sdwa v3, v247, sext(v3) dst_sel:DWORD dst_unused:UNUSED_PAD src0_sel:DWORD src1_sel:BYTE_0
	v_readlane_b32 s4, v255, 21
	v_and_b32_e32 v5, 32, v5
	v_bfe_i32 v14, v3, 0, 16
	v_readlane_b32 s5, v255, 22
	s_add_u32 s34, s44, s4
	v_add_lshl_u32 v3, v5, v14, 1
	s_addc_u32 s35, s45, s5
	s_add_i32 s56, s51, 0
	v_lshl_add_u32 v134, v4, 11, v3
	s_add_i32 m0, s56, 0x10000
	v_readlane_b32 s4, v255, 19
	global_load_lds_dwordx4 v134, s[34:35]
	s_add_i32 m0, s56, 0x12000
	s_add_u32 s16, s34, 0x40000
	global_load_lds_dwordx4 v130, s[34:35]
	s_addc_u32 s17, s35, 0
	s_add_i32 m0, s56, 0x14000
	v_readlane_b32 s5, v255, 20
	global_load_lds_dwordx4 v134, s[16:17]
	s_add_i32 m0, s56, 0x16000
	s_add_u32 s30, s42, s4
	s_addc_u32 s31, s43, s5
	s_add_i32 s57, s56, 0x2000
	v_lshl_add_u32 v136, v2, 11, v3
	global_load_lds_dwordx4 v130, s[16:17]
	s_barrier
	s_mov_b32 m0, s56
	s_add_u32 s16, s30, 0x40000
	global_load_lds_dwordx4 v136, s[30:31]
	s_mov_b32 m0, s57
	s_addc_u32 s17, s31, 0
	s_add_i32 s58, s56, 0x4000
	global_load_lds_dwordx4 v132, s[30:31]
	s_mov_b32 m0, s58
	s_add_i32 s59, s56, 0x6000
	global_load_lds_dwordx4 v136, s[16:17]
	s_mov_b32 m0, s59
	v_mov_b32_e32 v135, v1
	global_load_lds_dwordx4 v132, s[16:17]
	v_mov_b32_e32 v131, v1
	v_mov_b32_e32 v137, v1
	v_mov_b32_e32 v133, v1
	s_cmp_eq_u32 s9, 1
	v_lshl_add_u64 v[8:9], s[34:35], 0, v[134:135]
	v_lshl_add_u64 v[6:7], s[34:35], 0, v[130:131]
	v_lshl_add_u64 v[2:3], s[30:31], 0, v[136:137]
	s_cselect_b64 s[16:17], -1, 0
	s_cmp_lg_u32 s9, 1
	v_lshl_add_u64 v[4:5], s[30:31], 0, v[132:133]
	s_cbranch_scc1 .LBB0_851
	s_barrier
